# instruction selection in the VALU-bound mixer loops: paired bf16 conversions stored with ds_write_b16 + ds_write_b16_d16_hi, attention row-sum chains without +0 adds / self-max, back-to-back duplicate
# speedup vs baseline: 1.0041x; 1.0041x over previous
; DI bf16_t f2bf(float f) { return (bf16_t)(pk2(f, 0.f) & 0xffffu); }
; DI float exps(float x) { return __builtin_amdgcn_exp2f(fminf(x, 115.f)); }
; template <int MX, bool OUT>
; DI void rec_chunk(const Params& p, int l, int b, int h, int dir, int T0, unsigned char* smem, f32x4 (&St)[4], float& nst, float& dtot, int tid, const RecRaw& raw) {
;     ...
;       const float ig = raw.ig, fg = raw.fg;
;       const float lfs = (fg < -20.f) ? fg * 1.4426950408889634f : -__log2f(1.f + __expf(-fg));
;       const float ei = __expf(ig) * 0.125f;
; #pragma unroll
;       for (int i = 0; i < 8; ++i) {
; #pragma unroll
;         for (int hh = 0; hh < 2; ++hh) {
;           const int k = 2 * i + hh;
;           lf[k] = lfs;
;           kin[k] = __uint_as_float(hh ? (au[i] & 0xffff0000u) : (au[i] << 16)) * ei;
;           qv[k] = __uint_as_float(hh ? (bu[i] & 0xffff0000u) : (bu[i] << 16));
;           vv[k] = __uint_as_float(hh ? (cu[i] & 0xffff0000u) : (cu[i] << 16));
;     ...
;     const int mid = dir == 0 ? 31 : 32, last = dir == 0 ? 63 : 0;
;     const int kvbase = k0 * 128 + (tt & 7) * 2, t3 = tt >> 3;
;     float s_qm = 0.f, s_km = 0.f, s_qs = 0.f, s_ke = 0.f, s_dec = 0.f;
;     if (MX == 1) {
;       const float c = CUM[tt * 64], cm = CUM[mid * 64], cl = CUM[last * 64];
;       s_qm = exps(c - cm); s_km = exps(cm - c); s_qs = exps(c); s_ke = exps(cl - c); s_dec = exps(cl);
;     }
;     unsigned qm[8], km[8], qs[8];
; #pragma unroll
;     for (int i = 0; i < 8; ++i) {
;       float r_qm[2], r_km[2], r_qs[2];
; #pragma unroll
;       for (int hh = 0; hh < 2; ++hh) {
;         const int k = 2 * i + hh;
;         float e_qm, e_km, e_qs, e_ke, e_dec;
;         if (MX == 1) { e_qm = s_qm; e_km = s_km; e_qs = s_qs; e_ke = s_ke; e_dec = s_dec; }
;         else {
;           const float c = CUM[tt * 64 + k0 + k], cm = CUM[mid * 64 + k0 + k], cl = CUM[last * 64 + k0 + k];
;           e_qm = exps(c - cm); e_km = exps(cm - c); e_qs = exps(c); e_ke = exps(cl - c); e_dec = (tt == 0) ? exps(cl) : 0.f;
;         }
;         r_qm[hh] = qv[k] * e_qm;
;         r_km[hh] = kin[k] * e_km;
;         r_qs[hh] = qv[k] * e_qs;
;         const float ke = kin[k] * e_ke;
;         const int toff = kvbase + k * 128 + ((t3 ^ ((k >> 1) & 7)) << 4);
;         *(bf16_t*)(smem + L_KET + toff) = f2bf(ke);
;         *(bf16_t*)(smem + L_VT + toff) = f2bf(vv[k]);
;         if (tt == 0) DEC[k0 + k] = e_dec;
.LBB0_468:
	s_or_b64 exec, exec, s[34:35]
	v_mul_f32_e32 v52, 0x3fb8aa3b, v52
	v_exp_f32_e32 v53, v52
	v_mov_b32_e32 v52, s27
	s_waitcnt lgkmcnt(0)
	s_barrier
	s_nop 0
	ds_read_b32 v88, v57
	ds_read_b32 v52, v52
	v_mul_f32_e32 v89, 0x3e000000, v53
	v_lshlrev_b32_e32 v53, 16, v40
	v_mul_f32_e32 v53, v89, v53
	v_and_b32_e32 v40, 0xffff0000, v40
	s_waitcnt lgkmcnt(0)
	v_sub_f32_e32 v88, v52, v88
	v_min_f32_e32 v88, 0x42e60000, v88
	v_exp_f32_e32 v88, v88
	v_lshlrev_b32_e32 v90, 16, v44
	v_mul_f32_e32 v91, v89, v40
	v_and_b32_e32 v40, 0xffff0000, v44
	v_mul_f32_e32 v44, v53, v88
	v_cvt_pk_bf16_f32 v44, v44, s0
	ds_write_b16 v62, v44 offset:40960
	v_cvt_pk_bf16_f32 v44, v90, s0
	ds_write_b16 v62, v44 offset:49152
	v_mul_f32_e32 v44, v91, v88
	s_and_saveexec_b64 s[22:23], s[10:11]
	s_xor_b64 s[22:23], exec, s[22:23]
	s_cbranch_execz .LBB0_470
	v_cvt_pk_bf16_f32 v44, v44, s0
	v_cvt_pk_bf16_f32 v40, v40, s0
	ds_write_b16 v62, v44 offset:41088
	ds_write_b16 v62, v40 offset:49280

; DI bf16_t f2bf(float f) { return (bf16_t)(pk2(f, 0.f) & 0xffffu); }
; DI float exps(float x) { return __builtin_amdgcn_exp2f(fminf(x, 115.f)); }
; template <int MX, bool OUT>
; DI void rec_chunk(const Params& p, int l, int b, int h, int dir, int T0, unsigned char* smem, f32x4 (&St)[4], float& nst, float& dtot, int tid, const RecRaw& raw) {
;     ...
;         else {
;           const float c = CUM[tt * 64 + k0 + k], cm = CUM[mid * 64 + k0 + k], cl = CUM[last * 64 + k0 + k];
;           e_qm = exps(c - cm); e_km = exps(cm - c); e_qs = exps(c); e_ke = exps(cl - c); e_dec = (tt == 0) ? exps(cl) : 0.f;
;         }
;         r_qm[hh] = qv[k] * e_qm;
;         r_km[hh] = kin[k] * e_km;
;         r_qs[hh] = qv[k] * e_qs;
;         const float ke = kin[k] * e_ke;
;         const int toff = kvbase + k * 128 + ((t3 ^ ((k >> 1) & 7)) << 4);
;         *(bf16_t*)(smem + L_KET + toff) = f2bf(ke);
;         *(bf16_t*)(smem + L_VT + toff) = f2bf(vv[k]);
;         if (tt == 0) DEC[k0 + k] = e_dec;
.LBB0_531:
	s_or_b64 exec, exec, s[22:23]
	v_mul_f32_e32 v44, v109, v118
	v_mul_f32_e32 v45, v44, v120
	ds_read_b32 v47, v70 offset:8
	ds_read_b32 v44, v74 offset:8
	v_mul_f32_e32 v43, v45, v43
	v_and_b32_e32 v36, 0xffff0000, v36
	v_mul_f32_e32 v46, v117, v124
	v_mul_f32_e32 v46, v46, v123
	s_waitcnt lgkmcnt(0)
	v_sub_f32_e32 v45, v44, v47
	v_min_f32_e32 v45, 0x42e60000, v45
	v_exp_f32_e32 v45, v45
	v_cvt_pk_bf16_f32 v43, v43, v36
	ds_write_b16 v76, v43 offset:41088
	ds_write_b16_d16_hi v76, v43 offset:49280
	v_mul_f32_e32 v36, v46, v45
	v_lshlrev_b32_e32 v52, 16, v37
	v_cvt_pk_bf16_f32 v36, v36, s0
	ds_write_b16 v77, v36 offset:41216
	v_cvt_pk_bf16_f32 v36, v52, s0
	ds_write_b16 v77, v36 offset:49408
	s_and_saveexec_b64 s[22:23], s[14:15]
	s_xor_b64 s[22:23], exec, s[22:23]
	s_cbranch_execz .LBB0_533
	ds_read_b32 v36, v70 offset:12
	ds_read_b32 v43, v74 offset:12
	s_waitcnt lgkmcnt(0)
	v_sub_f32_e32 v36, v43, v36
	v_min_f32_e32 v36, 0x42e60000, v36
	v_exp_f32_e32 v36, v36

; DI bf16_t f2bf(float f) { return (bf16_t)(pk2(f, 0.f) & 0xffffu); }
; DI float exps(float x) { return __builtin_amdgcn_exp2f(fminf(x, 115.f)); }
; template <int MX, bool OUT>
; DI void rec_chunk(const Params& p, int l, int b, int h, int dir, int T0, unsigned char* smem, f32x4 (&St)[4], float& nst, float& dtot, int tid, const RecRaw& raw) {
;     ...
;         else {
;           const float c = CUM[tt * 64 + k0 + k], cm = CUM[mid * 64 + k0 + k], cl = CUM[last * 64 + k0 + k];
;           e_qm = exps(c - cm); e_km = exps(cm - c); e_qs = exps(c); e_ke = exps(cl - c); e_dec = (tt == 0) ? exps(cl) : 0.f;
;         }
;         r_qm[hh] = qv[k] * e_qm;
;         r_km[hh] = kin[k] * e_km;
;         r_qs[hh] = qv[k] * e_qs;
;         const float ke = kin[k] * e_ke;
;         const int toff = kvbase + k * 128 + ((t3 ^ ((k >> 1) & 7)) << 4);
;         *(bf16_t*)(smem + L_KET + toff) = f2bf(ke);
;         *(bf16_t*)(smem + L_VT + toff) = f2bf(vv[k]);
;         if (tt == 0) DEC[k0 + k] = e_dec;
.LBB0_535:
	s_or_b64 exec, exec, s[22:23]
	v_and_b32_e32 v44, 0xffff0000, v37
	ds_read_b32 v46, v70 offset:16
	ds_read_b32 v37, v74 offset:16
	v_mul_f32_e32 v43, v103, v112
	v_mul_f32_e32 v43, v43, v114
	v_mul_f32_e32 v36, v43, v36
	v_mul_f32_e32 v45, v111, v121
	s_waitcnt lgkmcnt(0)
	v_sub_f32_e32 v43, v37, v46
	v_min_f32_e32 v43, 0x42e60000, v43
	v_exp_f32_e32 v43, v43
	v_mul_f32_e32 v45, v45, v119
	v_cvt_pk_bf16_f32 v44, v44, v36
	ds_write_b16_d16_hi v77, v44 offset:41344
	ds_write_b16 v77, v44 offset:49536
	v_mul_f32_e32 v36, v45, v43
	v_lshlrev_b32_e32 v47, 16, v38
	v_cvt_pk_bf16_f32 v36, v36, s0
	ds_write_b16 v78, v36 offset:41472
	v_cvt_pk_bf16_f32 v36, v47, s0
	ds_write_b16 v78, v36 offset:49664
	s_and_saveexec_b64 s[22:23], s[14:15]
	s_xor_b64 s[22:23], exec, s[22:23]
	s_cbranch_execz .LBB0_537
	ds_read_b32 v36, v70 offset:20
	ds_read_b32 v37, v74 offset:20
	s_waitcnt lgkmcnt(0)
	v_sub_f32_e32 v36, v37, v36
	v_min_f32_e32 v36, 0x42e60000, v36
	v_exp_f32_e32 v36, v36

; DI bf16_t f2bf(float f) { return (bf16_t)(pk2(f, 0.f) & 0xffffu); }
; DI float exps(float x) { return __builtin_amdgcn_exp2f(fminf(x, 115.f)); }
; template <int MX, bool OUT>
; DI void rec_chunk(const Params& p, int l, int b, int h, int dir, int T0, unsigned char* smem, f32x4 (&St)[4], float& nst, float& dtot, int tid, const RecRaw& raw) {
;     ...
;         else {
;           const float c = CUM[tt * 64 + k0 + k], cm = CUM[mid * 64 + k0 + k], cl = CUM[last * 64 + k0 + k];
;           e_qm = exps(c - cm); e_km = exps(cm - c); e_qs = exps(c); e_ke = exps(cl - c); e_dec = (tt == 0) ? exps(cl) : 0.f;
;         }
;         r_qm[hh] = qv[k] * e_qm;
;         r_km[hh] = kin[k] * e_km;
;         r_qs[hh] = qv[k] * e_qs;
;         const float ke = kin[k] * e_ke;
;         const int toff = kvbase + k * 128 + ((t3 ^ ((k >> 1) & 7)) << 4);
;         *(bf16_t*)(smem + L_KET + toff) = f2bf(ke);
;         *(bf16_t*)(smem + L_VT + toff) = f2bf(vv[k]);
;         if (tt == 0) DEC[k0 + k] = e_dec;
.LBB0_539:
	s_or_b64 exec, exec, s[22:23]
	v_mul_f32_e32 v37, v97, v106
	v_mul_f32_e32 v43, v37, v108
	ds_read_b32 v45, v70 offset:24
	ds_read_b32 v37, v74 offset:24
	v_mul_f32_e32 v36, v43, v36
	v_mul_f32_e32 v44, v105, v115
	v_and_b32_e32 v38, 0xffff0000, v38
	v_mul_f32_e32 v44, v44, v113
	s_waitcnt lgkmcnt(0)
	v_sub_f32_e32 v43, v37, v45
	v_min_f32_e32 v43, 0x42e60000, v43
	v_exp_f32_e32 v43, v43
	v_cvt_pk_bf16_f32 v38, v38, v36
	ds_write_b16_d16_hi v78, v38 offset:41600
	ds_write_b16 v78, v38 offset:49792
	v_mul_f32_e32 v36, v44, v43
	v_lshlrev_b32_e32 v46, 16, v39
	v_cvt_pk_bf16_f32 v36, v36, s0
	ds_write_b16 v79, v36 offset:41728
	v_cvt_pk_bf16_f32 v36, v46, s0
	ds_write_b16 v79, v36 offset:49920
	s_and_saveexec_b64 s[22:23], s[14:15]
	s_xor_b64 s[22:23], exec, s[22:23]
	s_cbranch_execz .LBB0_541
	ds_read_b32 v36, v70 offset:28
	ds_read_b32 v37, v74 offset:28
	s_waitcnt lgkmcnt(0)
	v_sub_f32_e32 v36, v37, v36
	v_min_f32_e32 v36, 0x42e60000, v36
	v_exp_f32_e32 v36, v36

; DI bf16_t f2bf(float f) { return (bf16_t)(pk2(f, 0.f) & 0xffffu); }
; DI float exps(float x) { return __builtin_amdgcn_exp2f(fminf(x, 115.f)); }
; template <int MX, bool OUT>
; DI void rec_chunk(const Params& p, int l, int b, int h, int dir, int T0, unsigned char* smem, f32x4 (&St)[4], float& nst, float& dtot, int tid, const RecRaw& raw) {
;     ...
;         else {
;           const float c = CUM[tt * 64 + k0 + k], cm = CUM[mid * 64 + k0 + k], cl = CUM[last * 64 + k0 + k];
;           e_qm = exps(c - cm); e_km = exps(cm - c); e_qs = exps(c); e_ke = exps(cl - c); e_dec = (tt == 0) ? exps(cl) : 0.f;
;         }
;         r_qm[hh] = qv[k] * e_qm;
;         r_km[hh] = kin[k] * e_km;
;         r_qs[hh] = qv[k] * e_qs;
;         const float ke = kin[k] * e_ke;
;         const int toff = kvbase + k * 128 + ((t3 ^ ((k >> 1) & 7)) << 4);
;         *(bf16_t*)(smem + L_KET + toff) = f2bf(ke);
;         *(bf16_t*)(smem + L_VT + toff) = f2bf(vv[k]);
;         if (tt == 0) DEC[k0 + k] = e_dec;
.LBB0_543:
	s_or_b64 exec, exec, s[22:23]
	v_mul_f32_e32 v37, v92, v100
	v_mul_f32_e32 v38, v37, v102
	ds_read_b32 v44, v70 offset:32
	ds_read_b32 v37, v74 offset:32
	v_mul_f32_e32 v36, v38, v36
	v_mul_f32_e32 v43, v99, v110
	v_and_b32_e32 v39, 0xffff0000, v39
	v_mul_f32_e32 v43, v43, v107
	s_waitcnt lgkmcnt(0)
	v_sub_f32_e32 v38, v37, v44
	v_min_f32_e32 v38, 0x42e60000, v38
	v_exp_f32_e32 v38, v38
	v_cvt_pk_bf16_f32 v39, v39, v36
	ds_write_b16_d16_hi v79, v39 offset:41856
	ds_write_b16 v79, v39 offset:50048
	v_mul_f32_e32 v36, v43, v38
	v_lshlrev_b32_e32 v45, 16, v32
	v_cvt_pk_bf16_f32 v36, v36, s0
	ds_write_b16 v80, v36 offset:41984
	v_cvt_pk_bf16_f32 v36, v45, s0
	ds_write_b16 v80, v36 offset:50176
	s_and_saveexec_b64 s[22:23], s[14:15]
	s_xor_b64 s[22:23], exec, s[22:23]
	s_cbranch_execz .LBB0_545
	ds_read_b32 v36, v70 offset:36
	ds_read_b32 v37, v74 offset:36
	s_waitcnt lgkmcnt(0)
	v_sub_f32_e32 v36, v37, v36
	v_min_f32_e32 v36, 0x42e60000, v36
	v_exp_f32_e32 v36, v36

; DI bf16_t f2bf(float f) { return (bf16_t)(pk2(f, 0.f) & 0xffffu); }
; DI float exps(float x) { return __builtin_amdgcn_exp2f(fminf(x, 115.f)); }
; template <int MX, bool OUT>
; DI void rec_chunk(const Params& p, int l, int b, int h, int dir, int T0, unsigned char* smem, f32x4 (&St)[4], float& nst, float& dtot, int tid, const RecRaw& raw) {
;     ...
;         else {
;           const float c = CUM[tt * 64 + k0 + k], cm = CUM[mid * 64 + k0 + k], cl = CUM[last * 64 + k0 + k];
;           e_qm = exps(c - cm); e_km = exps(cm - c); e_qs = exps(c); e_ke = exps(cl - c); e_dec = (tt == 0) ? exps(cl) : 0.f;
;         }
;         r_qm[hh] = qv[k] * e_qm;
;         r_km[hh] = kin[k] * e_km;
;         r_qs[hh] = qv[k] * e_qs;
;         const float ke = kin[k] * e_ke;
;         const int toff = kvbase + k * 128 + ((t3 ^ ((k >> 1) & 7)) << 4);
;         *(bf16_t*)(smem + L_KET + toff) = f2bf(ke);
;         *(bf16_t*)(smem + L_VT + toff) = f2bf(vv[k]);
;         if (tt == 0) DEC[k0 + k] = e_dec;
.LBB0_547:
	s_or_b64 exec, exec, s[22:23]
	v_mul_f32_e32 v37, v66, v94
	v_mul_f32_e32 v38, v37, v96
	ds_read_b32 v43, v70 offset:40
	ds_read_b32 v37, v74 offset:40
	v_mul_f32_e32 v36, v38, v36
	v_and_b32_e32 v32, 0xffff0000, v32
	v_mul_f32_e32 v39, v93, v104
	v_mul_f32_e32 v39, v39, v101
	s_waitcnt lgkmcnt(0)
	v_sub_f32_e32 v38, v37, v43
	v_min_f32_e32 v38, 0x42e60000, v38
	v_exp_f32_e32 v38, v38
	v_cvt_pk_bf16_f32 v36, v36, v32
	ds_write_b16 v80, v36 offset:42112
	ds_write_b16_d16_hi v80, v36 offset:50304
	v_mul_f32_e32 v32, v39, v38
	v_lshlrev_b32_e32 v44, 16, v33
	v_cvt_pk_bf16_f32 v32, v32, s0
	ds_write_b16 v81, v32 offset:42240
	v_cvt_pk_bf16_f32 v32, v44, s0
	ds_write_b16 v81, v32 offset:50432
	s_and_saveexec_b64 s[22:23], s[14:15]
	s_xor_b64 s[22:23], exec, s[22:23]
	s_cbranch_execz .LBB0_549
	ds_read_b32 v32, v70 offset:44
	ds_read_b32 v36, v74 offset:44
	s_waitcnt lgkmcnt(0)
	v_sub_f32_e32 v32, v36, v32
	v_min_f32_e32 v32, 0x42e60000, v32
	v_exp_f32_e32 v32, v32

; DI bf16_t f2bf(float f) { return (bf16_t)(pk2(f, 0.f) & 0xffffu); }
; DI float exps(float x) { return __builtin_amdgcn_exp2f(fminf(x, 115.f)); }
; template <int MX, bool OUT>
; DI void rec_chunk(const Params& p, int l, int b, int h, int dir, int T0, unsigned char* smem, f32x4 (&St)[4], float& nst, float& dtot, int tid, const RecRaw& raw) {
;     ...
;         else {
;           const float c = CUM[tt * 64 + k0 + k], cm = CUM[mid * 64 + k0 + k], cl = CUM[last * 64 + k0 + k];
;           e_qm = exps(c - cm); e_km = exps(cm - c); e_qs = exps(c); e_ke = exps(cl - c); e_dec = (tt == 0) ? exps(cl) : 0.f;
;         }
;         r_qm[hh] = qv[k] * e_qm;
;         r_km[hh] = kin[k] * e_km;
;         r_qs[hh] = qv[k] * e_qs;
;         const float ke = kin[k] * e_ke;
;         const int toff = kvbase + k * 128 + ((t3 ^ ((k >> 1) & 7)) << 4);
;         *(bf16_t*)(smem + L_KET + toff) = f2bf(ke);
;         *(bf16_t*)(smem + L_VT + toff) = f2bf(vv[k]);
;         if (tt == 0) DEC[k0 + k] = e_dec;
.LBB0_551:
	s_or_b64 exec, exec, s[22:23]
	v_and_b32_e32 v37, 0xffff0000, v33
	ds_read_b32 v39, v70 offset:48
	ds_read_b32 v33, v74 offset:48
	v_mul_f32_e32 v36, v49, v90
	v_mul_f32_e32 v36, v36, v91
	v_mul_f32_e32 v32, v36, v32
	v_mul_f32_e32 v38, v67, v98
	s_waitcnt lgkmcnt(0)
	v_sub_f32_e32 v36, v33, v39
	v_min_f32_e32 v36, 0x42e60000, v36
	v_exp_f32_e32 v36, v36
	v_mul_f32_e32 v38, v38, v95
	v_cvt_pk_bf16_f32 v37, v37, v32
	ds_write_b16_d16_hi v81, v37 offset:42368
	ds_write_b16 v81, v37 offset:50560
	v_mul_f32_e32 v32, v38, v36
	v_lshlrev_b32_e32 v43, 16, v34
	v_cvt_pk_bf16_f32 v32, v32, s0
	ds_write_b16 v82, v32 offset:42496
	v_cvt_pk_bf16_f32 v32, v43, s0
	ds_write_b16 v82, v32 offset:50688
	s_and_saveexec_b64 s[22:23], s[14:15]
	s_xor_b64 s[22:23], exec, s[22:23]
	s_cbranch_execz .LBB0_553
	ds_read_b32 v32, v70 offset:52
	ds_read_b32 v33, v74 offset:52
	s_waitcnt lgkmcnt(0)
	v_sub_f32_e32 v32, v33, v32
	v_min_f32_e32 v32, 0x42e60000, v32
	v_exp_f32_e32 v32, v32

; DI bf16_t f2bf(float f) { return (bf16_t)(pk2(f, 0.f) & 0xffffu); }
; DI float exps(float x) { return __builtin_amdgcn_exp2f(fminf(x, 115.f)); }
; template <int MX, bool OUT>
; DI void rec_chunk(const Params& p, int l, int b, int h, int dir, int T0, unsigned char* smem, f32x4 (&St)[4], float& nst, float& dtot, int tid, const RecRaw& raw) {
;     ...
;         else {
;           const float c = CUM[tt * 64 + k0 + k], cm = CUM[mid * 64 + k0 + k], cl = CUM[last * 64 + k0 + k];
;           e_qm = exps(c - cm); e_km = exps(cm - c); e_qs = exps(c); e_ke = exps(cl - c); e_dec = (tt == 0) ? exps(cl) : 0.f;
;         }
;         r_qm[hh] = qv[k] * e_qm;
;         r_km[hh] = kin[k] * e_km;
;         r_qs[hh] = qv[k] * e_qs;
;         const float ke = kin[k] * e_ke;
;         const int toff = kvbase + k * 128 + ((t3 ^ ((k >> 1) & 7)) << 4);
;         *(bf16_t*)(smem + L_KET + toff) = f2bf(ke);
;         *(bf16_t*)(smem + L_VT + toff) = f2bf(vv[k]);
;         if (tt == 0) DEC[k0 + k] = e_dec;
.LBB0_555:
	s_or_b64 exec, exec, s[22:23]
	v_mul_f32_e32 v33, v48, v51
	v_mul_f32_e32 v36, v33, v63
	ds_read_b32 v38, v70 offset:56
	ds_read_b32 v33, v74 offset:56
	v_mul_f32_e32 v32, v36, v32
	v_mul_f32_e32 v37, v50, v65
	v_and_b32_e32 v34, 0xffff0000, v34
	v_mul_f32_e32 v37, v37, v64
	s_waitcnt lgkmcnt(0)
	v_sub_f32_e32 v36, v33, v38
	v_min_f32_e32 v36, 0x42e60000, v36
	v_exp_f32_e32 v36, v36
	v_cvt_pk_bf16_f32 v34, v34, v32
	ds_write_b16_d16_hi v82, v34 offset:42624
	ds_write_b16 v82, v34 offset:50816
	v_mul_f32_e32 v32, v37, v36
	v_lshlrev_b32_e32 v39, 16, v35
	v_cvt_pk_bf16_f32 v32, v32, s0
	ds_write_b16 v83, v32 offset:42752
	v_cvt_pk_bf16_f32 v32, v39, s0
	ds_write_b16 v83, v32 offset:50944
	s_and_saveexec_b64 s[22:23], s[14:15]
	s_xor_b64 s[22:23], exec, s[22:23]
	s_cbranch_execz .LBB0_557
	ds_read_b32 v32, v70 offset:60
	ds_read_b32 v33, v74 offset:60
	s_waitcnt lgkmcnt(0)
	v_sub_f32_e32 v32, v33, v32
	v_min_f32_e32 v32, 0x42e60000, v32
	v_exp_f32_e32 v32, v32

; DI bf16_t f2bf(float f) { return (bf16_t)(pk2(f, 0.f) & 0xffffu); }
; #define MFMA16(a, b, c) __builtin_amdgcn_mfma_f32_16x16x32_bf16((a), (b), (c), 0, 0, 0)
; template <int MX, bool OUT>
; DI void rec_chunk(const Params& p, int l, int b, int h, int dir, int T0, unsigned char* smem, f32x4 (&St)[4], float& nst, float& dtot, int tid, const RecRaw& raw) {
;     ...
;         const float ke = kin[k] * e_ke;
;         const int toff = kvbase + k * 128 + ((t3 ^ ((k >> 1) & 7)) << 4);
;         *(bf16_t*)(smem + L_KET + toff) = f2bf(ke);
;         *(bf16_t*)(smem + L_VT + toff) = f2bf(vv[k]);
;         if (tt == 0) DEC[k0 + k] = e_dec;
;     ...
;   {
; #pragma unroll
;     for (int c = 0; c < 4; ++c) {
;       const float d = DEC[16 * c + col];
; #pragma unroll
;       for (int j = 0; j < 4; ++j) St[c][j] *= d;
;     }
; #pragma unroll
;     for (int ks = 0; ks < 2; ++ks) {
;       const bf16x8 fa = *(const bf16x8*)(smem + L_VT + swz(16 * w + col, ks * 4 + g));
; #pragma unroll
;       for (int c = 0; c < 4; ++c) {
;         const bf16x8 fb = *(const bf16x8*)(smem + L_KET + swz(16 * c + col, ks * 4 + g));
;         St[c] = MFMA16(fa, fb, St[c]);
;       }
;     }
.LBB0_559:
	s_or_b64 exec, exec, s[22:23]
	v_mul_f32_e32 v33, v40, v41
	v_mul_f32_e32 v33, v33, v42
	v_mul_f32_e32 v32, v33, v32
	v_and_b32_e32 v34, 0xffff0000, v35
	v_cvt_pk_bf16_f32 v32, v32, v34
	ds_write_b16 v83, v32 offset:42880
	ds_write_b16_d16_hi v83, v32 offset:51072
	s_waitcnt lgkmcnt(0)
	s_barrier
	ds_read2_b32 v[32:33], v84 offset1:16
	v_add_u32_e32 v40, v85, v87
	ds_read_b128 v[36:39], v40 offset:40960
	s_waitcnt lgkmcnt(0)
	v_pk_mul_f32 v[8:9], v[8:9], v[32:33] op_sel_hi:[1,0]
	v_pk_mul_f32 v[10:11], v[10:11], v[32:33] op_sel_hi:[1,0]
	v_mov_b32_e32 v32, v33
	v_pk_mul_f32 v[28:29], v[28:29], v[32:33] op_sel_hi:[1,0]
	v_pk_mul_f32 v[30:31], v[30:31], v[32:33] op_sel_hi:[1,0]
	ds_read2_b32 v[32:33], v84 offset0:32 offset1:48
	s_waitcnt lgkmcnt(0)
	v_pk_mul_f32 v[16:17], v[16:17], v[32:33] op_sel_hi:[1,0]
	v_pk_mul_f32 v[18:19], v[18:19], v[32:33] op_sel_hi:[1,0]
	v_mov_b32_e32 v32, v33
	v_pk_mul_f32 v[12:13], v[12:13], v[32:33] op_sel_hi:[1,0]
	v_pk_mul_f32 v[14:15], v[14:15], v[32:33] op_sel_hi:[1,0]
	v_add_u32_e32 v32, v86, v87
	ds_read_b128 v[32:35], v32 offset:49152
	s_waitcnt lgkmcnt(0)
	v_mfma_f32_16x16x32_bf16 v[8:11], v[32:35], v[36:39], v[8:11]
	ds_read_b128 v[36:39], v40 offset:43008
	s_waitcnt lgkmcnt(0)
	v_mfma_f32_16x16x32_bf16 v[28:31], v[32:35], v[36:39], v[28:31]
	ds_read_b128 v[36:39], v40 offset:45056
	s_waitcnt lgkmcnt(0)
	v_mfma_f32_16x16x32_bf16 v[16:19], v[32:35], v[36:39], v[16:19]
	ds_read_b128 v[36:39], v40 offset:47104
	v_add_u32_e32 v40, v85, v88
	s_waitcnt lgkmcnt(0)
	v_mfma_f32_16x16x32_bf16 v[12:15], v[32:35], v[36:39], v[12:15]
	v_add_u32_e32 v32, v86, v88
	ds_read_b128 v[32:35], v32 offset:49152
	ds_read_b128 v[36:39], v40 offset:40960
	s_waitcnt lgkmcnt(0)
	v_mfma_f32_16x16x32_bf16 v[8:11], v[32:35], v[36:39], v[8:11]
	ds_read_b128 v[36:39], v40 offset:43008
	s_waitcnt lgkmcnt(0)
	v_mfma_f32_16x16x32_bf16 v[28:31], v[32:35], v[36:39], v[28:31]
	ds_read_b128 v[36:39], v40 offset:45056
	s_waitcnt lgkmcnt(0)
	v_mfma_f32_16x16x32_bf16 v[16:19], v[32:35], v[36:39], v[16:19]
	ds_read_b128 v[36:39], v40 offset:47104
	s_waitcnt lgkmcnt(0)
	v_mfma_f32_16x16x32_bf16 v[12:15], v[32:35], v[36:39], v[12:15]
	s_and_saveexec_b64 s[22:23], s[4:5]
	s_cbranch_execz .LBB0_561
	ds_read_b32 v32, v89
	s_waitcnt lgkmcnt(0)
	v_mul_f32_e32 v59, v59, v32

; DI bf16_t f2bf(float f) { return (bf16_t)(pk2(f, 0.f) & 0xffffu); }
; DI float exps(float x) { return __builtin_amdgcn_exp2f(fminf(x, 115.f)); }
; template <int MX, bool OUT>
; DI void rec_chunk(const Params& p, int l, int b, int h, int dir, int T0, unsigned char* smem, f32x4 (&St)[4], float& nst, float& dtot, int tid, const RecRaw& raw) {
;     ...
;     const int mid = dir == 0 ? 31 : 32, last = dir == 0 ? 63 : 0;
;     const int kvbase = k0 * 128 + (tt & 7) * 2, t3 = tt >> 3;
;     float s_qm = 0.f, s_km = 0.f, s_qs = 0.f, s_ke = 0.f, s_dec = 0.f;
;     if (MX == 1) {
;       const float c = CUM[tt * 64], cm = CUM[mid * 64], cl = CUM[last * 64];
;       s_qm = exps(c - cm); s_km = exps(cm - c); s_qs = exps(c); s_ke = exps(cl - c); s_dec = exps(cl);
;     }
;     unsigned qm[8], km[8], qs[8];
; #pragma unroll
;     for (int i = 0; i < 8; ++i) {
;       float r_qm[2], r_km[2], r_qs[2];
; #pragma unroll
;       for (int hh = 0; hh < 2; ++hh) {
;         const int k = 2 * i + hh;
;         float e_qm, e_km, e_qs, e_ke, e_dec;
;         if (MX == 1) { e_qm = s_qm; e_km = s_km; e_qs = s_qs; e_ke = s_ke; e_dec = s_dec; }
;         else {
;           const float c = CUM[tt * 64 + k0 + k], cm = CUM[mid * 64 + k0 + k], cl = CUM[last * 64 + k0 + k];
;           e_qm = exps(c - cm); e_km = exps(cm - c); e_qs = exps(c); e_ke = exps(cl - c); e_dec = (tt == 0) ? exps(cl) : 0.f;
;         }
;         r_qm[hh] = qv[k] * e_qm;
;         r_km[hh] = kin[k] * e_km;
;         r_qs[hh] = qv[k] * e_qs;
;         const float ke = kin[k] * e_ke;
;         const int toff = kvbase + k * 128 + ((t3 ^ ((k >> 1) & 7)) << 4);
;         *(bf16_t*)(smem + L_KET + toff) = f2bf(ke);
;         *(bf16_t*)(smem + L_VT + toff) = f2bf(vv[k]);
;         if (tt == 0) DEC[k0 + k] = e_dec;
.LBB0_631:
	s_or_b64 exec, exec, s[46:47]
	v_mov_b32_e32 v66, s53
	v_mov_b32_e32 v67, s54
	s_waitcnt lgkmcnt(0)
	s_barrier
	s_nop 0
	ds_read_b32 v65, v130
	ds_read_b32 v66, v66
	ds_read_b32 v67, v67
	v_mul_f32_e32 v64, 0x3fb8aa3b, v64
	v_exp_f32_e32 v64, v64
	v_lshlrev_b32_e32 v70, 16, v60
	v_cvt_pk_bf16_f32 v70, v70, s0
	s_waitcnt lgkmcnt(0)
	v_sub_f32_e32 v69, v67, v65
	v_min_f32_e32 v69, 0x42e60000, v69
	v_exp_f32_e32 v69, v69
	v_max_f32_e32 v67, v67, v67
	v_min_f32_e32 v67, 0x42e60000, v67
	v_mul_f32_e32 v68, 0x3e000000, v64
	v_lshlrev_b32_e32 v64, 16, v56
	v_exp_f32_e32 v67, v67
	v_mul_f32_e32 v64, v68, v64
	v_mul_f32_e32 v71, v64, v69
	v_cvt_pk_bf16_f32 v71, v71, s0
	ds_write_b16 v132, v71 offset:40960
	ds_write_b16 v132, v70 offset:49152
	s_and_saveexec_b64 s[0:1], s[8:9]
	v_add_u32_e32 v70, 0x10000, v131
	ds_write_b32 v70, v67
	s_or_b64 exec, exec, s[0:1]
	v_and_b32_e32 v56, 0xffff0000, v56
	v_mul_f32_e32 v56, v68, v56
	v_and_b32_e32 v60, 0xffff0000, v60
	v_mul_f32_e32 v70, v56, v69
	v_cvt_pk_bf16_f32 v70, v70, v60
	ds_write_b16 v132, v70 offset:41088
	ds_write_b16_d16_hi v132, v70 offset:49280
	s_and_saveexec_b64 s[0:1], s[8:9]
	v_add_u32_e32 v60, 0x10004, v131
	ds_write_b32 v60, v67
	s_or_b64 exec, exec, s[0:1]
	v_lshlrev_b32_e32 v60, 16, v57
	v_mul_f32_e32 v60, v68, v60
	v_lshlrev_b32_e32 v70, 16, v61
	v_mul_f32_e32 v71, v60, v69
	v_cvt_pk_bf16_f32 v71, v71, v70
	ds_write_b16 v133, v71 offset:41216
	ds_write_b16_d16_hi v133, v71 offset:49408
	s_and_saveexec_b64 s[0:1], s[8:9]
	v_add_u32_e32 v70, 0x10008, v131
	ds_write_b32 v70, v67
	s_or_b64 exec, exec, s[0:1]
	v_and_b32_e32 v57, 0xffff0000, v57
	v_mul_f32_e32 v57, v68, v57
	v_and_b32_e32 v61, 0xffff0000, v61
	v_mul_f32_e32 v70, v57, v69
	v_cvt_pk_bf16_f32 v70, v70, v61
	ds_write_b16 v133, v70 offset:41344
	ds_write_b16_d16_hi v133, v70 offset:49536
	s_and_saveexec_b64 s[0:1], s[8:9]
	v_add_u32_e32 v61, 0x1000c, v131
	ds_write_b32 v61, v67
	s_or_b64 exec, exec, s[0:1]
	v_lshlrev_b32_e32 v61, 16, v58
	v_mul_f32_e32 v61, v68, v61
	v_lshlrev_b32_e32 v70, 16, v62
	v_mul_f32_e32 v71, v61, v69
	v_cvt_pk_bf16_f32 v71, v71, v70
	ds_write_b16 v134, v71 offset:41472
	ds_write_b16_d16_hi v134, v71 offset:49664
	s_and_saveexec_b64 s[0:1], s[8:9]
	v_add_u32_e32 v70, 0x10010, v131
	ds_write_b32 v70, v67
	s_or_b64 exec, exec, s[0:1]
	v_and_b32_e32 v58, 0xffff0000, v58
	v_mul_f32_e32 v58, v68, v58
	v_and_b32_e32 v62, 0xffff0000, v62
	v_mul_f32_e32 v70, v58, v69
	v_cvt_pk_bf16_f32 v70, v70, v62
	ds_write_b16 v134, v70 offset:41600
	ds_write_b16_d16_hi v134, v70 offset:49792
	s_and_saveexec_b64 s[0:1], s[8:9]
	v_add_u32_e32 v62, 0x10014, v131
	ds_write_b32 v62, v67
	s_or_b64 exec, exec, s[0:1]
	v_lshlrev_b32_e32 v62, 16, v59
	v_mul_f32_e32 v62, v68, v62
	v_lshlrev_b32_e32 v70, 16, v63
	v_mul_f32_e32 v71, v62, v69
	v_cvt_pk_bf16_f32 v71, v71, v70
	ds_write_b16 v135, v71 offset:41728
	ds_write_b16_d16_hi v135, v71 offset:49920
	s_and_saveexec_b64 s[0:1], s[8:9]
	v_add_u32_e32 v70, 0x10018, v131
	ds_write_b32 v70, v67
	s_or_b64 exec, exec, s[0:1]
	v_and_b32_e32 v59, 0xffff0000, v59
	v_mul_f32_e32 v59, v68, v59
	v_and_b32_e32 v63, 0xffff0000, v63
	v_mul_f32_e32 v70, v59, v69
	v_cvt_pk_bf16_f32 v70, v70, v63
	ds_write_b16 v135, v70 offset:41856
	ds_write_b16_d16_hi v135, v70 offset:50048
	s_and_saveexec_b64 s[0:1], s[8:9]
	v_add_u32_e32 v63, 0x1001c, v131
	ds_write_b32 v63, v67
	s_or_b64 exec, exec, s[0:1]
	v_lshlrev_b32_e32 v63, 16, v48
	v_mul_f32_e32 v63, v68, v63
	v_lshlrev_b32_e32 v70, 16, v52
	v_mul_f32_e32 v71, v63, v69
	v_cvt_pk_bf16_f32 v71, v71, v70
	ds_write_b16 v136, v71 offset:41984
	ds_write_b16_d16_hi v136, v71 offset:50176
	s_and_saveexec_b64 s[0:1], s[8:9]
	v_add_u32_e32 v70, 0x10020, v131
	ds_write_b32 v70, v67
	s_or_b64 exec, exec, s[0:1]
	v_and_b32_e32 v48, 0xffff0000, v48
	v_mul_f32_e32 v48, v68, v48
	v_and_b32_e32 v52, 0xffff0000, v52
	v_mul_f32_e32 v70, v48, v69
	v_cvt_pk_bf16_f32 v70, v70, v52
	ds_write_b16 v136, v70 offset:42112
	ds_write_b16_d16_hi v136, v70 offset:50304
	s_and_saveexec_b64 s[0:1], s[8:9]
	v_add_u32_e32 v52, 0x10024, v131
	ds_write_b32 v52, v67
	s_or_b64 exec, exec, s[0:1]
	v_lshlrev_b32_e32 v52, 16, v49
	v_mul_f32_e32 v52, v68, v52
	v_lshlrev_b32_e32 v70, 16, v53
	v_mul_f32_e32 v71, v52, v69
	v_cvt_pk_bf16_f32 v71, v71, v70
	ds_write_b16 v137, v71 offset:42240
	ds_write_b16_d16_hi v137, v71 offset:50432
	s_and_saveexec_b64 s[0:1], s[8:9]
	v_add_u32_e32 v70, 0x10028, v131
	ds_write_b32 v70, v67
	s_or_b64 exec, exec, s[0:1]
	v_and_b32_e32 v49, 0xffff0000, v49
	v_mul_f32_e32 v49, v68, v49
	v_and_b32_e32 v53, 0xffff0000, v53
	v_mul_f32_e32 v70, v49, v69
	v_cvt_pk_bf16_f32 v70, v70, v53
	ds_write_b16 v137, v70 offset:42368
	ds_write_b16_d16_hi v137, v70 offset:50560
	s_and_saveexec_b64 s[0:1], s[8:9]
	v_add_u32_e32 v53, 0x1002c, v131
	ds_write_b32 v53, v67
	s_or_b64 exec, exec, s[0:1]
	v_lshlrev_b32_e32 v53, 16, v50
	v_mul_f32_e32 v53, v68, v53
	v_lshlrev_b32_e32 v70, 16, v54
	v_mul_f32_e32 v71, v53, v69
	v_cvt_pk_bf16_f32 v71, v71, v70
	ds_write_b16 v138, v71 offset:42496
	ds_write_b16_d16_hi v138, v71 offset:50688
	s_and_saveexec_b64 s[0:1], s[8:9]
	v_add_u32_e32 v70, 0x10030, v131
	ds_write_b32 v70, v67
	s_or_b64 exec, exec, s[0:1]
	v_and_b32_e32 v50, 0xffff0000, v50
; template <int MX, bool OUT>
; DI void rec_chunk(const Params& p, int l, int b, int h, int dir, int T0, unsigned char* smem, f32x4 (&St)[4], float& nst, float& dtot, int tid, const RecRaw& raw) {
;     ...
;       const float c = CUM[tt * 64], cm = CUM[mid * 64], cl = CUM[last * 64];
;       s_qm = exps(c - cm); s_km = exps(cm - c); s_qs = exps(c); s_ke = exps(cl - c); s_dec = exps(cl);
;     }
;     unsigned qm[8], km[8], qs[8];
; #pragma unroll
;     for (int i = 0; i < 8; ++i) {
;       float r_qm[2], r_km[2], r_qs[2];
; #pragma unroll
;       for (int hh = 0; hh < 2; ++hh) {
;         const int k = 2 * i + hh;
;         float e_qm, e_km, e_qs, e_ke, e_dec;
;         if (MX == 1) { e_qm = s_qm; e_km = s_km; e_qs = s_qs; e_ke = s_ke; e_dec = s_dec; }
;         else {
;           const float c = CUM[tt * 64 + k0 + k], cm = CUM[mid * 64 + k0 + k], cl = CUM[last * 64 + k0 + k];
;           e_qm = exps(c - cm); e_km = exps(cm - c); e_qs = exps(c); e_ke = exps(cl - c); e_dec = (tt == 0) ? exps(cl) : 0.f;
;         }
;         r_qm[hh] = qv[k] * e_qm;
;         r_km[hh] = kin[k] * e_km;
;         r_qs[hh] = qv[k] * e_qs;
;         const float ke = kin[k] * e_ke;
;         const int toff = kvbase + k * 128 + ((t3 ^ ((k >> 1) & 7)) << 4);
;         *(bf16_t*)(smem + L_KET + toff) = f2bf(ke);
;         *(bf16_t*)(smem + L_VT + toff) = f2bf(vv[k]);
;         if (tt == 0) DEC[k0 + k] = e_dec;
;       }
;       qm[i] = pk2(r_qm[0], r_qm[1]); km[i] = pk2(r_km[0], r_km[1]); qs[i] = pk2(r_qs[0], r_qs[1]);
;     }
;     if (OUT) {
;       *(uint4*)(smem + L_QM + swz(tt, grp * 2)) = make_uint4(qm[0], qm[1], qm[2], qm[3]);
;       *(uint4*)(smem + L_QM + swz(tt, grp * 2 + 1)) = make_uint4(qm[4], qm[5], qm[6], qm[7]);
;       *(uint4*)(smem + L_KM + swz(tt, grp * 2)) = make_uint4(km[0], km[1], km[2], km[3]);
;       *(uint4*)(smem + L_KM + swz(tt, grp * 2 + 1)) = make_uint4(km[4], km[5], km[6], km[7]);
;       *(uint4*)(smem + L_QS + swz(tt, grp * 2)) = make_uint4(qs[0], qs[1], qs[2], qs[3]);
;       *(uint4*)(smem + L_QS + swz(tt, grp * 2 + 1)) = make_uint4(qs[4], qs[5], qs[6], qs[7]);
;     }
;     ...
; #pragma unroll
;     for (int a = 0; a < 4; ++a) {
;       S[a] = f32x4{0.f, 0.f, 0.f, 0.f};
;       const bool need = dir == 0 ? (a <= w) : (a >= w);
;       if (need) {
; #pragma unroll
;         for (int ks = 0; ks < 2; ++ks) {
	v_mul_f32_e32 v50, v68, v50
	v_and_b32_e32 v54, 0xffff0000, v54
	v_mul_f32_e32 v70, v50, v69
	v_cvt_pk_bf16_f32 v70, v70, v54
	ds_write_b16 v138, v70 offset:42624
	ds_write_b16_d16_hi v138, v70 offset:50816
	s_and_saveexec_b64 s[0:1], s[8:9]
	v_add_u32_e32 v54, 0x10034, v131
	ds_write_b32 v54, v67
	s_or_b64 exec, exec, s[0:1]
	v_lshlrev_b32_e32 v54, 16, v51
	v_mul_f32_e32 v54, v68, v54
	v_lshlrev_b32_e32 v70, 16, v55
	v_mul_f32_e32 v71, v54, v69
	v_cvt_pk_bf16_f32 v71, v71, v70
	ds_write_b16 v139, v71 offset:42752
	ds_write_b16_d16_hi v139, v71 offset:50944
	s_and_saveexec_b64 s[0:1], s[8:9]
	v_add_u32_e32 v70, 0x10038, v131
	ds_write_b32 v70, v67
	s_or_b64 exec, exec, s[0:1]
	v_and_b32_e32 v51, 0xffff0000, v51
	v_mul_f32_e32 v51, v68, v51
	v_and_b32_e32 v55, 0xffff0000, v55
	v_mul_f32_e32 v68, v51, v69
	v_cvt_pk_bf16_f32 v68, v68, v55
	ds_write_b16 v139, v68 offset:42880
	ds_write_b16_d16_hi v139, v68 offset:51072
	s_and_saveexec_b64 s[0:1], s[8:9]
	v_add_u32_e32 v55, 0x1003c, v131
	ds_write_b32 v55, v67
	s_or_b64 exec, exec, s[0:1]
	v_sub_f32_e32 v55, v65, v66
	v_min_f32_e32 v55, 0x42e60000, v55
	v_exp_f32_e32 v69, v55
	v_sub_f32_e32 v55, v66, v65
	v_min_f32_e32 v55, 0x42e60000, v55
	v_exp_f32_e32 v70, v55
	v_max_f32_e32 v55, v65, v65
	v_min_f32_e32 v55, 0x42e60000, v55
	v_exp_f32_e32 v65, v55
	v_and_b32_e32 v55, 0xffff0000, v47
	v_mul_f32_e32 v71, v69, v55
	v_lshlrev_b32_e32 v47, 16, v47
	v_mul_f32_e32 v72, v65, v55
	v_and_b32_e32 v55, 0xffff0000, v46
	v_lshlrev_b32_e32 v46, 16, v46
	v_mul_f32_e32 v66, v69, v55
	v_mul_f32_e32 v50, v50, v70
	v_mul_f32_e32 v55, v65, v55
	v_mul_f32_e32 v53, v53, v70
	v_mul_f32_e32 v68, v65, v46
	v_mul_f32_e32 v73, v69, v47
	v_mul_f32_e32 v75, v65, v47
	v_and_b32_e32 v47, 0xffff0000, v45
	v_lshlrev_b32_e32 v45, 16, v45
	v_mul_f32_e32 v67, v69, v46
	v_cvt_pk_bf16_f32 v50, v53, v50
	v_cvt_pk_bf16_f32 v68, v68, v55
	v_mul_f32_e32 v53, v69, v47
	v_mul_f32_e32 v47, v65, v47
	v_mul_f32_e32 v55, v65, v45
	v_cvt_pk_bf16_f32 v46, v67, v66
	v_mul_f32_e32 v49, v49, v70
	v_mul_f32_e32 v52, v52, v70
	v_cvt_pk_bf16_f32 v67, v55, v47
	v_and_b32_e32 v47, 0xffff0000, v44
	v_lshlrev_b32_e32 v44, 16, v44
	v_mul_f32_e32 v74, v54, v70
	v_mul_f32_e32 v54, v69, v45
	v_cvt_pk_bf16_f32 v49, v52, v49
	v_mul_f32_e32 v52, v69, v47
	v_mul_f32_e32 v47, v65, v47
	v_mul_f32_e32 v55, v65, v44
	v_cvt_pk_bf16_f32 v45, v54, v53
	v_mul_f32_e32 v53, v69, v44
	v_cvt_pk_bf16_f32 v66, v55, v47
	v_and_b32_e32 v47, 0xffff0000, v43
	v_lshlrev_b32_e32 v43, 16, v43
	v_mul_f32_e32 v48, v48, v70
	v_mul_f32_e32 v54, v63, v70
	v_cvt_pk_bf16_f32 v44, v53, v52
	v_mul_f32_e32 v52, v69, v47
	v_mul_f32_e32 v53, v59, v70
	v_mul_f32_e32 v47, v65, v47
	v_mul_f32_e32 v59, v65, v43
	v_cvt_pk_bf16_f32 v48, v54, v48
	v_mul_f32_e32 v54, v69, v43
	v_mul_f32_e32 v55, v62, v70
	v_cvt_pk_bf16_f32 v59, v59, v47
	v_and_b32_e32 v47, 0xffff0000, v42
	v_lshlrev_b32_e32 v42, 16, v42
	v_cvt_pk_bf16_f32 v43, v54, v52
	v_cvt_pk_bf16_f32 v55, v55, v53
	v_mul_f32_e32 v52, v69, v47
	v_mul_f32_e32 v53, v58, v70
	v_mul_f32_e32 v47, v65, v47
	v_mul_f32_e32 v54, v69, v42
	v_mul_f32_e32 v58, v61, v70
	v_mul_f32_e32 v61, v65, v42
	v_cvt_pk_bf16_f32 v42, v54, v52
	v_cvt_pk_bf16_f32 v54, v58, v53
	v_cvt_pk_bf16_f32 v58, v61, v47
	v_and_b32_e32 v47, 0xffff0000, v41
	v_lshlrev_b32_e32 v41, 16, v41
	v_mul_f32_e32 v52, v69, v47
	v_mul_f32_e32 v53, v57, v70
	v_mul_f32_e32 v47, v65, v47
	v_mul_f32_e32 v57, v69, v41
	v_mul_f32_e32 v61, v65, v41
	v_mul_f32_e32 v60, v60, v70
	v_cvt_pk_bf16_f32 v41, v57, v52
	v_cvt_pk_bf16_f32 v57, v61, v47
	v_and_b32_e32 v47, 0xffff0000, v40
	v_lshlrev_b32_e32 v40, 16, v40
	v_cvt_pk_bf16_f32 v53, v60, v53
	v_mul_f32_e32 v52, v69, v47
	v_mul_f32_e32 v56, v56, v70
	v_mul_f32_e32 v47, v65, v47
	v_mul_f32_e32 v60, v69, v40
	v_mul_f32_e32 v61, v64, v70
	v_mul_f32_e32 v62, v65, v40
	v_mul_f32_e32 v51, v51, v70
	v_cvt_pk_bf16_f32 v40, v60, v52
	v_cvt_pk_bf16_f32 v52, v61, v56
	v_cvt_pk_bf16_f32 v56, v62, v47
	v_cvt_pk_bf16_f32 v47, v73, v71
	v_cvt_pk_bf16_f32 v51, v74, v51
	v_cvt_pk_bf16_f32 v69, v75, v72
	ds_write_b128 v140, v[40:43] offset:16384
	ds_write_b128 v141, v[44:47] offset:16384
	ds_write_b128 v140, v[52:55] offset:24576
	ds_write_b128 v141, v[48:51] offset:24576
	ds_write_b128 v140, v[56:59] offset:32768
	ds_write_b128 v141, v[66:69] offset:32768
	v_mov_b32_e32 v40, 0
	v_add_u32_e32 v238, v142, v147
	v_add_u32_e32 v240, v143, v147
	v_add_u32_e32 v237, v142, v148
	v_add_u32_e32 v239, v143, v148
	v_mov_b32_e32 v44, 0
	v_mov_b32_e32 v45, 0
	v_mov_b32_e32 v46, 0
	v_mov_b32_e32 v47, 0
	s_waitcnt lgkmcnt(0)
	s_barrier
	s_and_saveexec_b64 s[0:1], s[68:69]
	s_cbranch_execz .LBB0_667
	ds_read_b128 v[42:45], v238 offset:24576
	ds_read_b128 v[46:49], v240 offset:16384
	ds_read_b128 v[50:53], v237 offset:24576
	s_waitcnt lgkmcnt(1)
	v_mfma_f32_16x16x32_bf16 v[42:45], v[42:45], v[46:49], 0
	ds_read_b128 v[46:49], v239 offset:16384
	s_waitcnt lgkmcnt(0)
	v_mfma_f32_16x16x32_bf16 v[44:47], v[50:53], v[46:49], v[42:45]
	s_and_saveexec_b64 s[46:47], s[6:7]
	s_nop 6
	v_cndmask_b32_e64 v44, 0, v44, s[90:91]
	v_cndmask_b32_e64 v45, 0, v45, s[92:93]
	v_cndmask_b32_e64 v46, 0, v46, s[94:95]
	v_cndmask_b32_e64 v47, 0, v47, s[96:97]
	s_or_b64 exec, exec, s[46:47]

; DI bf16_t f2bf(float f) { return (bf16_t)(pk2(f, 0.f) & 0xffffu); }
; DI float exps(float x) { return __builtin_amdgcn_exp2f(fminf(x, 115.f)); }
; template <int MX, bool OUT>
; DI void rec_chunk(const Params& p, int l, int b, int h, int dir, int T0, unsigned char* smem, f32x4 (&St)[4], float& nst, float& dtot, int tid, const RecRaw& raw) {
;     ...
;     const int mid = dir == 0 ? 31 : 32, last = dir == 0 ? 63 : 0;
;     const int kvbase = k0 * 128 + (tt & 7) * 2, t3 = tt >> 3;
;     float s_qm = 0.f, s_km = 0.f, s_qs = 0.f, s_ke = 0.f, s_dec = 0.f;
;     if (MX == 1) {
;       const float c = CUM[tt * 64], cm = CUM[mid * 64], cl = CUM[last * 64];
;       s_qm = exps(c - cm); s_km = exps(cm - c); s_qs = exps(c); s_ke = exps(cl - c); s_dec = exps(cl);
;     }
;     unsigned qm[8], km[8], qs[8];
; #pragma unroll
;     for (int i = 0; i < 8; ++i) {
;       float r_qm[2], r_km[2], r_qs[2];
; #pragma unroll
;       for (int hh = 0; hh < 2; ++hh) {
;         const int k = 2 * i + hh;
;         float e_qm, e_km, e_qs, e_ke, e_dec;
;         if (MX == 1) { e_qm = s_qm; e_km = s_km; e_qs = s_qs; e_ke = s_ke; e_dec = s_dec; }
;         else {
;           const float c = CUM[tt * 64 + k0 + k], cm = CUM[mid * 64 + k0 + k], cl = CUM[last * 64 + k0 + k];
;           e_qm = exps(c - cm); e_km = exps(cm - c); e_qs = exps(c); e_ke = exps(cl - c); e_dec = (tt == 0) ? exps(cl) : 0.f;
;         }
;         r_qm[hh] = qv[k] * e_qm;
;         r_km[hh] = kin[k] * e_km;
;         r_qs[hh] = qv[k] * e_qs;
;         const float ke = kin[k] * e_ke;
;         const int toff = kvbase + k * 128 + ((t3 ^ ((k >> 1) & 7)) << 4);
;         *(bf16_t*)(smem + L_KET + toff) = f2bf(ke);
;         *(bf16_t*)(smem + L_VT + toff) = f2bf(vv[k]);
;         if (tt == 0) DEC[k0 + k] = e_dec;
.LBB0_876:
	s_or_b64 exec, exec, s[44:45]
	v_mov_b32_e32 v66, s56
	v_mov_b32_e32 v67, s57
	s_waitcnt lgkmcnt(0)
	s_barrier
	s_nop 0
	ds_read_b32 v65, v134
	ds_read_b32 v66, v66
	ds_read_b32 v67, v67
	v_mul_f32_e32 v64, 0x3fb8aa3b, v64
	v_exp_f32_e32 v64, v64
	v_lshlrev_b32_e32 v70, 16, v60
	v_cvt_pk_bf16_f32 v70, v70, s0
	s_waitcnt lgkmcnt(0)
	v_sub_f32_e32 v69, v67, v65
	v_min_f32_e32 v69, 0x42e60000, v69
	v_exp_f32_e32 v69, v69
	v_max_f32_e32 v67, v67, v67
	v_min_f32_e32 v67, 0x42e60000, v67
	v_mul_f32_e32 v68, 0x3e000000, v64
	v_lshlrev_b32_e32 v64, 16, v56
	v_exp_f32_e32 v67, v67
	v_mul_f32_e32 v64, v68, v64
	v_mul_f32_e32 v71, v64, v69
	v_cvt_pk_bf16_f32 v71, v71, s0
	ds_write_b16 v136, v71 offset:40960
	ds_write_b16 v136, v70 offset:49152
	s_and_saveexec_b64 s[0:1], s[8:9]
	v_add_u32_e32 v70, 0x10000, v135
	ds_write_b32 v70, v67
	s_or_b64 exec, exec, s[0:1]
	v_and_b32_e32 v56, 0xffff0000, v56
	v_mul_f32_e32 v56, v68, v56
	v_and_b32_e32 v60, 0xffff0000, v60
	v_mul_f32_e32 v70, v56, v69
	v_cvt_pk_bf16_f32 v70, v70, v60
	ds_write_b16 v136, v70 offset:41088
	ds_write_b16_d16_hi v136, v70 offset:49280
	s_and_saveexec_b64 s[0:1], s[8:9]
	v_add_u32_e32 v60, 0x10004, v135
	ds_write_b32 v60, v67
	s_or_b64 exec, exec, s[0:1]
	v_lshlrev_b32_e32 v60, 16, v57
	v_mul_f32_e32 v60, v68, v60
	v_lshlrev_b32_e32 v70, 16, v61
	v_mul_f32_e32 v71, v60, v69
	v_cvt_pk_bf16_f32 v71, v71, v70
	ds_write_b16 v137, v71 offset:41216
	ds_write_b16_d16_hi v137, v71 offset:49408
	s_and_saveexec_b64 s[0:1], s[8:9]
	v_add_u32_e32 v70, 0x10008, v135
	ds_write_b32 v70, v67
	s_or_b64 exec, exec, s[0:1]
	v_and_b32_e32 v57, 0xffff0000, v57
	v_mul_f32_e32 v57, v68, v57
	v_and_b32_e32 v61, 0xffff0000, v61
	v_mul_f32_e32 v70, v57, v69
	v_cvt_pk_bf16_f32 v70, v70, v61
	ds_write_b16 v137, v70 offset:41344
	ds_write_b16_d16_hi v137, v70 offset:49536
	s_and_saveexec_b64 s[0:1], s[8:9]
	v_add_u32_e32 v61, 0x1000c, v135
	ds_write_b32 v61, v67
	s_or_b64 exec, exec, s[0:1]
	v_lshlrev_b32_e32 v61, 16, v58
	v_mul_f32_e32 v61, v68, v61
	v_lshlrev_b32_e32 v70, 16, v62
	v_mul_f32_e32 v71, v61, v69
	v_cvt_pk_bf16_f32 v71, v71, v70
	ds_write_b16 v138, v71 offset:41472
	ds_write_b16_d16_hi v138, v71 offset:49664
	s_and_saveexec_b64 s[0:1], s[8:9]
	v_add_u32_e32 v70, 0x10010, v135
	ds_write_b32 v70, v67
	s_or_b64 exec, exec, s[0:1]
	v_and_b32_e32 v58, 0xffff0000, v58
	v_mul_f32_e32 v58, v68, v58
	v_and_b32_e32 v62, 0xffff0000, v62
	v_mul_f32_e32 v70, v58, v69
	v_cvt_pk_bf16_f32 v70, v70, v62
	ds_write_b16 v138, v70 offset:41600
	ds_write_b16_d16_hi v138, v70 offset:49792
	s_and_saveexec_b64 s[0:1], s[8:9]
	v_add_u32_e32 v62, 0x10014, v135
	ds_write_b32 v62, v67
	s_or_b64 exec, exec, s[0:1]
	v_lshlrev_b32_e32 v62, 16, v59
	v_mul_f32_e32 v62, v68, v62
	v_lshlrev_b32_e32 v70, 16, v63
	v_mul_f32_e32 v71, v62, v69
	v_cvt_pk_bf16_f32 v71, v71, v70
	ds_write_b16 v139, v71 offset:41728
	ds_write_b16_d16_hi v139, v71 offset:49920
	s_and_saveexec_b64 s[0:1], s[8:9]
	v_add_u32_e32 v70, 0x10018, v135
	ds_write_b32 v70, v67
	s_or_b64 exec, exec, s[0:1]
	v_and_b32_e32 v59, 0xffff0000, v59
	v_mul_f32_e32 v59, v68, v59
	v_and_b32_e32 v63, 0xffff0000, v63
	v_mul_f32_e32 v70, v59, v69
	v_cvt_pk_bf16_f32 v70, v70, v63
	ds_write_b16 v139, v70 offset:41856
	ds_write_b16_d16_hi v139, v70 offset:50048
	s_and_saveexec_b64 s[0:1], s[8:9]
	v_add_u32_e32 v63, 0x1001c, v135
	ds_write_b32 v63, v67
	s_or_b64 exec, exec, s[0:1]
	v_lshlrev_b32_e32 v63, 16, v48
	v_mul_f32_e32 v63, v68, v63
	v_lshlrev_b32_e32 v70, 16, v52
	v_mul_f32_e32 v71, v63, v69
	v_cvt_pk_bf16_f32 v71, v71, v70
	ds_write_b16 v140, v71 offset:41984
	ds_write_b16_d16_hi v140, v71 offset:50176
	s_and_saveexec_b64 s[0:1], s[8:9]
	v_add_u32_e32 v70, 0x10020, v135
	ds_write_b32 v70, v67
	s_or_b64 exec, exec, s[0:1]
	v_and_b32_e32 v48, 0xffff0000, v48
	v_mul_f32_e32 v48, v68, v48
	v_and_b32_e32 v52, 0xffff0000, v52
	v_mul_f32_e32 v70, v48, v69
	v_cvt_pk_bf16_f32 v70, v70, v52
	ds_write_b16 v140, v70 offset:42112
	ds_write_b16_d16_hi v140, v70 offset:50304
	s_and_saveexec_b64 s[0:1], s[8:9]
	v_add_u32_e32 v52, 0x10024, v135
	ds_write_b32 v52, v67
	s_or_b64 exec, exec, s[0:1]
	v_lshlrev_b32_e32 v52, 16, v49
	v_mul_f32_e32 v52, v68, v52
	v_lshlrev_b32_e32 v70, 16, v53
	v_mul_f32_e32 v71, v52, v69
	v_cvt_pk_bf16_f32 v71, v71, v70
	ds_write_b16 v141, v71 offset:42240
	ds_write_b16_d16_hi v141, v71 offset:50432
	s_and_saveexec_b64 s[0:1], s[8:9]
	v_add_u32_e32 v70, 0x10028, v135
	ds_write_b32 v70, v67
	s_or_b64 exec, exec, s[0:1]
	v_and_b32_e32 v49, 0xffff0000, v49
	v_mul_f32_e32 v49, v68, v49
	v_and_b32_e32 v53, 0xffff0000, v53
	v_mul_f32_e32 v70, v49, v69
	v_cvt_pk_bf16_f32 v70, v70, v53
	ds_write_b16 v141, v70 offset:42368
	ds_write_b16_d16_hi v141, v70 offset:50560
	s_and_saveexec_b64 s[0:1], s[8:9]
	v_add_u32_e32 v53, 0x1002c, v135
	ds_write_b32 v53, v67
	s_or_b64 exec, exec, s[0:1]
	v_lshlrev_b32_e32 v53, 16, v50
	v_mul_f32_e32 v53, v68, v53
	v_lshlrev_b32_e32 v70, 16, v54
	v_mul_f32_e32 v71, v53, v69
	v_cvt_pk_bf16_f32 v71, v71, v70
	ds_write_b16 v142, v71 offset:42496
	ds_write_b16_d16_hi v142, v71 offset:50688
	s_and_saveexec_b64 s[0:1], s[8:9]
	v_add_u32_e32 v70, 0x10030, v135
	ds_write_b32 v70, v67
	s_or_b64 exec, exec, s[0:1]
	v_and_b32_e32 v50, 0xffff0000, v50
; template <int MX, bool OUT>
; DI void rec_chunk(const Params& p, int l, int b, int h, int dir, int T0, unsigned char* smem, f32x4 (&St)[4], float& nst, float& dtot, int tid, const RecRaw& raw) {
;     ...
;       const float c = CUM[tt * 64], cm = CUM[mid * 64], cl = CUM[last * 64];
;       s_qm = exps(c - cm); s_km = exps(cm - c); s_qs = exps(c); s_ke = exps(cl - c); s_dec = exps(cl);
;     }
;     unsigned qm[8], km[8], qs[8];
; #pragma unroll
;     for (int i = 0; i < 8; ++i) {
;       float r_qm[2], r_km[2], r_qs[2];
; #pragma unroll
;       for (int hh = 0; hh < 2; ++hh) {
;         const int k = 2 * i + hh;
;         float e_qm, e_km, e_qs, e_ke, e_dec;
;         if (MX == 1) { e_qm = s_qm; e_km = s_km; e_qs = s_qs; e_ke = s_ke; e_dec = s_dec; }
;         else {
;           const float c = CUM[tt * 64 + k0 + k], cm = CUM[mid * 64 + k0 + k], cl = CUM[last * 64 + k0 + k];
;           e_qm = exps(c - cm); e_km = exps(cm - c); e_qs = exps(c); e_ke = exps(cl - c); e_dec = (tt == 0) ? exps(cl) : 0.f;
;         }
;         r_qm[hh] = qv[k] * e_qm;
;         r_km[hh] = kin[k] * e_km;
;         r_qs[hh] = qv[k] * e_qs;
;         const float ke = kin[k] * e_ke;
;         const int toff = kvbase + k * 128 + ((t3 ^ ((k >> 1) & 7)) << 4);
;         *(bf16_t*)(smem + L_KET + toff) = f2bf(ke);
;         *(bf16_t*)(smem + L_VT + toff) = f2bf(vv[k]);
;         if (tt == 0) DEC[k0 + k] = e_dec;
;       }
;       qm[i] = pk2(r_qm[0], r_qm[1]); km[i] = pk2(r_km[0], r_km[1]); qs[i] = pk2(r_qs[0], r_qs[1]);
;     }
;     if (OUT) {
;       *(uint4*)(smem + L_QM + swz(tt, grp * 2)) = make_uint4(qm[0], qm[1], qm[2], qm[3]);
;       *(uint4*)(smem + L_QM + swz(tt, grp * 2 + 1)) = make_uint4(qm[4], qm[5], qm[6], qm[7]);
;       *(uint4*)(smem + L_KM + swz(tt, grp * 2)) = make_uint4(km[0], km[1], km[2], km[3]);
;       *(uint4*)(smem + L_KM + swz(tt, grp * 2 + 1)) = make_uint4(km[4], km[5], km[6], km[7]);
;       *(uint4*)(smem + L_QS + swz(tt, grp * 2)) = make_uint4(qs[0], qs[1], qs[2], qs[3]);
;       *(uint4*)(smem + L_QS + swz(tt, grp * 2 + 1)) = make_uint4(qs[4], qs[5], qs[6], qs[7]);
;     }
;     ...
; #pragma unroll
;     for (int a = 0; a < 4; ++a) {
;       S[a] = f32x4{0.f, 0.f, 0.f, 0.f};
;       const bool need = dir == 0 ? (a <= w) : (a >= w);
;       if (need) {
; #pragma unroll
;         for (int ks = 0; ks < 2; ++ks) {
	v_mul_f32_e32 v50, v68, v50
	v_and_b32_e32 v54, 0xffff0000, v54
	v_mul_f32_e32 v70, v50, v69
	v_cvt_pk_bf16_f32 v70, v70, v54
	ds_write_b16 v142, v70 offset:42624
	ds_write_b16_d16_hi v142, v70 offset:50816
	s_and_saveexec_b64 s[0:1], s[8:9]
	v_add_u32_e32 v54, 0x10034, v135
	ds_write_b32 v54, v67
	s_or_b64 exec, exec, s[0:1]
	v_lshlrev_b32_e32 v54, 16, v51
	v_mul_f32_e32 v54, v68, v54
	v_lshlrev_b32_e32 v70, 16, v55
	v_mul_f32_e32 v71, v54, v69
	v_cvt_pk_bf16_f32 v71, v71, v70
	ds_write_b16 v143, v71 offset:42752
	ds_write_b16_d16_hi v143, v71 offset:50944
	s_and_saveexec_b64 s[0:1], s[8:9]
	v_add_u32_e32 v70, 0x10038, v135
	ds_write_b32 v70, v67
	s_or_b64 exec, exec, s[0:1]
	v_and_b32_e32 v51, 0xffff0000, v51
	v_mul_f32_e32 v51, v68, v51
	v_and_b32_e32 v55, 0xffff0000, v55
	v_mul_f32_e32 v68, v51, v69
	v_cvt_pk_bf16_f32 v68, v68, v55
	ds_write_b16 v143, v68 offset:42880
	ds_write_b16_d16_hi v143, v68 offset:51072
	s_and_saveexec_b64 s[0:1], s[8:9]
	v_add_u32_e32 v55, 0x1003c, v135
	ds_write_b32 v55, v67
	s_or_b64 exec, exec, s[0:1]
	v_sub_f32_e32 v55, v65, v66
	v_min_f32_e32 v55, 0x42e60000, v55
	v_exp_f32_e32 v69, v55
	v_sub_f32_e32 v55, v66, v65
	v_min_f32_e32 v55, 0x42e60000, v55
	v_exp_f32_e32 v70, v55
	v_max_f32_e32 v55, v65, v65
	v_min_f32_e32 v55, 0x42e60000, v55
	v_exp_f32_e32 v65, v55
	v_and_b32_e32 v55, 0xffff0000, v47
	v_mul_f32_e32 v71, v69, v55
	v_lshlrev_b32_e32 v47, 16, v47
	v_mul_f32_e32 v72, v65, v55
	v_and_b32_e32 v55, 0xffff0000, v46
	v_lshlrev_b32_e32 v46, 16, v46
	v_mul_f32_e32 v66, v69, v55
	v_mul_f32_e32 v50, v50, v70
	v_mul_f32_e32 v55, v65, v55
	v_mul_f32_e32 v53, v53, v70
	v_mul_f32_e32 v68, v65, v46
	v_mul_f32_e32 v73, v69, v47
	v_mul_f32_e32 v75, v65, v47
	v_and_b32_e32 v47, 0xffff0000, v45
	v_lshlrev_b32_e32 v45, 16, v45
	v_mul_f32_e32 v67, v69, v46
	v_cvt_pk_bf16_f32 v50, v53, v50
	v_cvt_pk_bf16_f32 v68, v68, v55
	v_mul_f32_e32 v53, v69, v47
	v_mul_f32_e32 v47, v65, v47
	v_mul_f32_e32 v55, v65, v45
	v_cvt_pk_bf16_f32 v46, v67, v66
	v_mul_f32_e32 v49, v49, v70
	v_mul_f32_e32 v52, v52, v70
	v_cvt_pk_bf16_f32 v67, v55, v47
	v_and_b32_e32 v47, 0xffff0000, v44
	v_lshlrev_b32_e32 v44, 16, v44
	v_mul_f32_e32 v74, v54, v70
	v_mul_f32_e32 v54, v69, v45
	v_cvt_pk_bf16_f32 v49, v52, v49
	v_mul_f32_e32 v52, v69, v47
	v_mul_f32_e32 v47, v65, v47
	v_mul_f32_e32 v55, v65, v44
	v_cvt_pk_bf16_f32 v45, v54, v53
	v_mul_f32_e32 v53, v69, v44
	v_cvt_pk_bf16_f32 v66, v55, v47
	v_and_b32_e32 v47, 0xffff0000, v43
	v_lshlrev_b32_e32 v43, 16, v43
	v_mul_f32_e32 v48, v48, v70
	v_mul_f32_e32 v54, v63, v70
	v_cvt_pk_bf16_f32 v44, v53, v52
	v_mul_f32_e32 v52, v69, v47
	v_mul_f32_e32 v53, v59, v70
	v_mul_f32_e32 v47, v65, v47
	v_mul_f32_e32 v59, v65, v43
	v_cvt_pk_bf16_f32 v48, v54, v48
	v_mul_f32_e32 v54, v69, v43
	v_mul_f32_e32 v55, v62, v70
	v_cvt_pk_bf16_f32 v59, v59, v47
	v_and_b32_e32 v47, 0xffff0000, v42
	v_lshlrev_b32_e32 v42, 16, v42
	v_cvt_pk_bf16_f32 v43, v54, v52
	v_cvt_pk_bf16_f32 v55, v55, v53
	v_mul_f32_e32 v52, v69, v47
	v_mul_f32_e32 v53, v58, v70
	v_mul_f32_e32 v47, v65, v47
	v_mul_f32_e32 v54, v69, v42
	v_mul_f32_e32 v58, v61, v70
	v_mul_f32_e32 v61, v65, v42
	v_cvt_pk_bf16_f32 v42, v54, v52
	v_cvt_pk_bf16_f32 v54, v58, v53
	v_cvt_pk_bf16_f32 v58, v61, v47
	v_and_b32_e32 v47, 0xffff0000, v41
	v_lshlrev_b32_e32 v41, 16, v41
	v_mul_f32_e32 v52, v69, v47
	v_mul_f32_e32 v53, v57, v70
	v_mul_f32_e32 v47, v65, v47
	v_mul_f32_e32 v57, v69, v41
	v_mul_f32_e32 v61, v65, v41
	v_mul_f32_e32 v60, v60, v70
	v_cvt_pk_bf16_f32 v41, v57, v52
	v_cvt_pk_bf16_f32 v57, v61, v47
	v_and_b32_e32 v47, 0xffff0000, v40
	v_lshlrev_b32_e32 v40, 16, v40
	v_cvt_pk_bf16_f32 v53, v60, v53
	v_mul_f32_e32 v52, v69, v47
	v_mul_f32_e32 v56, v56, v70
	v_mul_f32_e32 v47, v65, v47
	v_mul_f32_e32 v60, v69, v40
	v_mul_f32_e32 v61, v64, v70
	v_mul_f32_e32 v62, v65, v40
	v_mul_f32_e32 v51, v51, v70
	v_cvt_pk_bf16_f32 v40, v60, v52
	v_cvt_pk_bf16_f32 v52, v61, v56
	v_cvt_pk_bf16_f32 v56, v62, v47
	v_cvt_pk_bf16_f32 v47, v73, v71
	v_cvt_pk_bf16_f32 v51, v74, v51
	v_cvt_pk_bf16_f32 v69, v75, v72
	ds_write_b128 v144, v[40:43] offset:16384
	ds_write_b128 v145, v[44:47] offset:16384
	ds_write_b128 v144, v[52:55] offset:24576
	ds_write_b128 v145, v[48:51] offset:24576
	ds_write_b128 v144, v[56:59] offset:32768
	ds_write_b128 v145, v[66:69] offset:32768
	v_mov_b32_e32 v40, 0
	v_add_u32_e32 v240, v146, v151
	v_add_u32_e32 v242, v147, v151
	v_add_u32_e32 v239, v146, v152
	v_add_u32_e32 v241, v147, v152
	v_mov_b32_e32 v44, 0
	v_mov_b32_e32 v45, 0
	v_mov_b32_e32 v46, 0
	v_mov_b32_e32 v47, 0
	s_waitcnt lgkmcnt(0)
	s_barrier
	s_and_saveexec_b64 s[0:1], s[68:69]
	s_cbranch_execz .LBB0_912
	ds_read_b128 v[42:45], v240 offset:24576
	ds_read_b128 v[46:49], v242 offset:16384
	ds_read_b128 v[50:53], v239 offset:24576
	s_waitcnt lgkmcnt(1)
	v_mfma_f32_16x16x32_bf16 v[42:45], v[42:45], v[46:49], 0
	ds_read_b128 v[46:49], v241 offset:16384
	s_waitcnt lgkmcnt(0)
	v_mfma_f32_16x16x32_bf16 v[44:47], v[50:53], v[46:49], v[42:45]
	s_and_saveexec_b64 s[44:45], s[6:7]
	s_nop 6
	v_cndmask_b32_e64 v44, 0, v44, s[90:91]
	v_cndmask_b32_e64 v45, 0, v45, s[92:93]
	v_cndmask_b32_e64 v46, 0, v46, s[94:95]
	v_cndmask_b32_e64 v47, 0, v47, s[96:97]
	s_or_b64 exec, exec, s[44:45]
